# prompt attention chunk: output stores widened to 4x dwordx4 via v_permlane32_swap (was 8x dwordx2)
# speedup vs baseline: 1.0503x; 1.0033x over previous
.LBB0_728:
	s_or_b64 exec, exec, s[12:13]
	v_readfirstlane_b32 s14, v0
	s_cmp_ge_i32 s14, s22
	s_mov_b64 s[12:13], -1
	s_cbranch_scc1 .LBB0_723
	s_cmp_ge_i32 s14, s21
	v_lshlrev_b32_e32 v92, 1, v138
	v_mbcnt_hi_u32_b32 v102, -1, v220
	s_cbranch_scc0 .LBB0_731
	s_sub_i32 s12, s14, s21
	s_and_b32 s15, s12, 3
	s_lshl_b32 s13, s15, 5
	v_or_b32_e32 v0, s13, v154
	s_lshr_b32 s12, s12, 2
	v_ashrrev_i32_e32 v1, 31, v0
	v_readlane_b32 s24, v254, 54
	v_lshlrev_b64 v[84:85], 12, v[0:1]
	v_readlane_b32 s25, v254, 55
	s_add_i32 s12, s12, s23
	v_mov_b32_e32 v93, v131
	v_lshl_add_u64 v[0:1], s[24:25], 0, v[84:85]
	s_lshl_b32 s24, s12, 7
	s_mov_b32 s25, s92
	v_lshl_add_u64 v[0:1], v[0:1], 0, s[24:25]
	v_lshl_add_u64 v[90:91], v[0:1], 0, v[92:93]
	global_load_dwordx4 v[68:71], v[90:91], off
	global_load_dwordx4 v[64:67], v[90:91], off offset:32
	s_add_i32 s93, s15, 1
	v_lshl_or_b32 v4, s93, 5, v136
	v_mad_u32_u24 v94, v4, s16, v129
	ds_read_b128 v[16:19], v94
	ds_read_b128 v[76:79], v94 offset:32
	s_add_i32 s94, s15, 2
	v_lshl_or_b32 v20, s94, 5, v136
	v_mad_u32_u24 v95, v20, s16, v129
	v_or_b32_e32 v2, s13, v136
	s_add_i32 s95, s15, 3
	v_mad_u32_u24 v93, v2, s16, v129
	v_lshl_or_b32 v20, s95, 5, v136
	ds_read_b128 v[0:3], v93
	ds_read_b128 v[72:75], v93 offset:32
	v_mad_u32_u24 v96, v20, s16, v129
	s_mov_b32 s13, s92
	v_readlane_b32 s56, v254, 22
	s_or_b32 s24, s15, 4
	s_lshl_b64 vcc, s[12:13], 2
	v_readlane_b32 s58, v254, 24
	v_readlane_b32 s59, v254, 25
	s_add_u32 vcc_lo, s58, vcc_lo
	s_addc_u32 vcc_hi, s59, vcc_hi
	s_cmp_eq_u32 s15, 3
	v_readlane_b32 s57, v254, 23
	v_readlane_b32 s56, v255, 4
	v_readlane_b32 s57, v255, 5
	v_readlane_b32 s60, v254, 26
	v_readlane_b32 s61, v254, 27
	v_readlane_b32 s62, v254, 28
	v_readlane_b32 s63, v254, 29
	v_readlane_b32 s64, v254, 30
	v_readlane_b32 s65, v254, 31
	v_readlane_b32 s66, v254, 32
	v_readlane_b32 s67, v254, 33
	v_readlane_b32 s68, v254, 34
	v_readlane_b32 s69, v254, 35
	v_readlane_b32 s70, v254, 36
	v_readlane_b32 s71, v254, 37
	s_waitcnt vmcnt(1) lgkmcnt(3)
	v_mfma_f32_32x32x16_bf16 v[48:63], v[16:19], v[68:71], 0
	ds_read_b128 v[16:19], v95
	ds_read_b128 v[80:83], v95 offset:32
	s_waitcnt lgkmcnt(1)
	v_mfma_f32_32x32x16_bf16 v[32:47], v[16:19], v[68:71], 0
	ds_read_b128 v[16:19], v96
	ds_read_b128 v[86:89], v96 offset:32
	s_waitcnt vmcnt(0)
	v_mfma_f32_32x32x16_bf16 v[48:63], v[76:79], v[64:67], v[48:63]
	global_load_dwordx4 v[76:79], v[90:91], off offset:64
	v_mfma_f32_32x32x16_bf16 v[0:15], v[0:3], v[68:71], 0
	v_mfma_f32_32x32x16_bf16 v[0:15], v[72:75], v[64:67], v[0:15]
	global_load_dwordx4 v[72:75], v[90:91], off offset:96
	s_waitcnt lgkmcnt(1)
	v_mfma_f32_32x32x16_bf16 v[16:31], v[16:19], v[68:71], 0
	v_mfma_f32_32x32x16_bf16 v[32:47], v[80:83], v[64:67], v[32:47]
	s_waitcnt lgkmcnt(0)
	v_mfma_f32_32x32x16_bf16 v[16:31], v[86:89], v[64:67], v[16:31]
	ds_read_b128 v[86:89], v93 offset:64
	ds_read_b128 v[80:83], v93 offset:96
	s_waitcnt vmcnt(1) lgkmcnt(1)
	v_mfma_f32_32x32x16_bf16 v[0:15], v[86:89], v[76:79], v[0:15]
	ds_read_b128 v[86:89], v94 offset:64
	ds_read_b128 v[98:101], v94 offset:96
	s_waitcnt lgkmcnt(1)
	v_mfma_f32_32x32x16_bf16 v[48:63], v[86:89], v[76:79], v[48:63]
	ds_read_b128 v[86:89], v95 offset:64
	ds_read_b128 v[104:107], v95 offset:96
	s_waitcnt lgkmcnt(1)
	v_mfma_f32_32x32x16_bf16 v[32:47], v[86:89], v[76:79], v[32:47]
	ds_read_b128 v[86:89], v96 offset:64
	ds_read_b128 v[112:115], v96 offset:96
	global_load_dword v96, v131, vcc
	s_cselect_b64 vcc, -1, 0
	s_or_b64 vcc, s[8:9], vcc
	s_xor_b32 s13, s15, 2
	s_cmp_lt_u32 s13, 2
	s_waitcnt lgkmcnt(1)
	v_mfma_f32_32x32x16_bf16 v[16:31], v[86:89], v[76:79], v[16:31]
	s_waitcnt vmcnt(1)
	v_mfma_f32_32x32x16_bf16 v[48:63], v[98:101], v[72:75], v[48:63]
	v_mfma_f32_32x32x16_bf16 v[32:47], v[104:107], v[72:75], v[32:47]
	s_nop 10
	v_cndmask_b32_e32 v48, v179, v48, vcc
	v_cndmask_b32_e32 v49, v179, v49, vcc
	v_cndmask_b32_e32 v50, v179, v50, vcc
	v_cndmask_b32_e32 v51, v179, v51, vcc
	v_cndmask_b32_e32 v52, v179, v52, vcc
	v_cndmask_b32_e32 v53, v179, v53, vcc
	v_cndmask_b32_e32 v54, v179, v54, vcc
	s_waitcnt lgkmcnt(0)
	v_mfma_f32_32x32x16_bf16 v[16:31], v[112:115], v[72:75], v[16:31]
	v_cndmask_b32_e32 v55, v179, v55, vcc
	v_cndmask_b32_e32 v56, v179, v56, vcc
	v_cndmask_b32_e32 v57, v179, v57, vcc
	v_cndmask_b32_e32 v58, v179, v58, vcc
	v_cndmask_b32_e32 v59, v179, v59, vcc
	v_cndmask_b32_e32 v60, v179, v60, vcc
	v_cndmask_b32_e32 v61, v179, v61, vcc
	v_cndmask_b32_e32 v62, v179, v62, vcc
	v_cndmask_b32_e32 v116, v179, v63, vcc
	s_cselect_b64 vcc, -1, 0
	s_or_b64 vcc, s[8:9], vcc
	s_or_b32 s13, s15, s20
	s_cmp_eq_u32 s13, 0
	v_cndmask_b32_e32 v117, v179, v32, vcc
	v_cndmask_b32_e32 v118, v179, v33, vcc
	v_cndmask_b32_e32 v119, v179, v34, vcc
	v_cndmask_b32_e32 v120, v179, v35, vcc
	v_cndmask_b32_e32 v121, v179, v36, vcc
	v_cndmask_b32_e32 v122, v179, v37, vcc
	v_cndmask_b32_e32 v123, v179, v38, vcc
	v_cndmask_b32_e32 v130, v179, v39, vcc
	v_cndmask_b32_e32 v63, v179, v40, vcc
	v_cndmask_b32_e32 v111, v179, v41, vcc
	v_cndmask_b32_e32 v110, v179, v42, vcc
	v_cndmask_b32_e32 v109, v179, v43, vcc
	v_cndmask_b32_e32 v108, v179, v44, vcc
	v_cndmask_b32_e32 v107, v179, v45, vcc
	v_cndmask_b32_e32 v106, v179, v46, vcc
	v_cndmask_b32_e32 v105, v179, v47, vcc
	s_cselect_b64 vcc, -1, 0
	v_cndmask_b32_e32 v103, v17, v179, vcc
	v_and_b32_e32 v17, 64, v102
	v_cndmask_b32_e32 v104, v16, v179, vcc
	v_xor_b32_e32 v16, 32, v102
	v_add_u32_e32 v17, 64, v17
	v_cndmask_b32_e32 v101, v18, v179, vcc
	v_cndmask_b32_e32 v100, v19, v179, vcc
	v_cndmask_b32_e32 v99, v20, v179, vcc
	v_cndmask_b32_e32 v98, v21, v179, vcc
	v_cndmask_b32_e32 v97, v22, v179, vcc
	v_cndmask_b32_e32 v95, v23, v179, vcc
	v_cndmask_b32_e32 v94, v24, v179, vcc
	v_cndmask_b32_e32 v93, v25, v179, vcc
	v_cndmask_b32_e32 v91, v26, v179, vcc
	v_cndmask_b32_e32 v90, v27, v179, vcc
	v_cndmask_b32_e32 v86, v28, v179, vcc
	v_cndmask_b32_e32 v87, v29, v179, vcc
	v_cndmask_b32_e32 v88, v30, v179, vcc
	v_cndmask_b32_e32 v89, v31, v179, vcc
	v_cmp_lt_i32_e32 vcc, v16, v17
	v_mfma_f32_32x32x16_bf16 v[0:15], v[80:83], v[72:75], v[0:15]
	s_mov_b32 s13, 0x3fb8aa3b
	v_cndmask_b32_e32 v44, v102, v16, vcc
	v_lshl_or_b32 v16, s24, 5, v136
	v_mad_u32_u24 v40, v16, s16, v129
	ds_read_b128 v[16:19], v40
	ds_read_b128 v[32:35], v40 offset:32
	ds_read_b128 v[36:39], v40 offset:64
	ds_read_b128 v[40:43], v40 offset:96
	v_lshlrev_b32_e32 v112, 2, v44
	s_waitcnt lgkmcnt(3)
	v_mfma_f32_32x32x16_bf16 v[16:31], v[16:19], v[68:71], 0
	s_nop 0
	v_cndmask_b32_e64 v0, v179, v0, s[26:27]
	v_cndmask_b32_e64 v1, v179, v1, s[28:29]
	v_max3_f32 v45, v0, s17, v1
	v_cndmask_b32_e64 v2, v179, v2, s[30:31]
	v_cndmask_b32_e64 v3, v179, v3, s[34:35]
	v_cndmask_b32_e64 v4, v179, v4, s[36:37]
	v_cndmask_b32_e64 v5, v179, v5, s[38:39]
	s_waitcnt lgkmcnt(2)
	v_mfma_f32_32x32x16_bf16 v[16:31], v[32:35], v[64:67], v[16:31]
	v_max3_f32 v32, v45, v2, v3
	v_max3_f32 v32, v32, v4, v5
	v_cndmask_b32_e64 v6, v179, v6, s[96:97]
	v_cndmask_b32_e64 v7, v179, v7, s[2:3]
	v_max3_f32 v32, v32, v6, v7
	v_cndmask_b32_e64 v8, v179, v8, s[72:73]
	v_cndmask_b32_e64 v9, v179, v9, s[74:75]
	s_waitcnt lgkmcnt(1)
	v_mfma_f32_32x32x16_bf16 v[16:31], v[36:39], v[76:79], v[16:31]
	v_max3_f32 v32, v32, v8, v9
	v_cndmask_b32_e64 v34, v179, v10, s[76:77]
	v_cndmask_b32_e64 v11, v179, v11, s[78:79]
	v_max3_f32 v10, v32, v34, v11
	v_cndmask_b32_e64 v12, v179, v12, s[80:81]
	v_cndmask_b32_e64 v13, v179, v13, s[82:83]
	v_max3_f32 v10, v10, v12, v13
	s_waitcnt lgkmcnt(0)
	v_mfma_f32_32x32x16_bf16 v[16:31], v[40:43], v[72:75], v[16:31]
	v_cndmask_b32_e64 v14, v179, v14, s[84:85]
	v_cndmask_b32_e64 v15, v179, v15, s[86:87]
	v_max3_f32 v10, v10, v14, v15
	v_max3_f32 v10, v10, v48, v49
	v_max3_f32 v10, v10, v50, v51
	v_max3_f32 v10, v10, v52, v53
	v_max3_f32 v10, v10, v54, v55
	s_nop 4
	v_cndmask_b32_e64 v16, v16, v179, s[56:57]
	v_readlane_b32 s56, v255, 34
	v_readlane_b32 s57, v255, 35
	v_max3_f32 v10, v10, v56, v57
	v_max3_f32 v10, v10, v58, v59
	v_cndmask_b32_e64 v17, v179, v17, s[56:57]
	v_readlane_b32 s56, v255, 8
	v_readlane_b32 s57, v255, 9
	v_max3_f32 v10, v10, v60, v61
	v_max3_f32 v10, v10, v62, v116
	v_cndmask_b32_e64 v18, v18, v179, s[56:57]
	v_readlane_b32 s56, v255, 10
	v_readlane_b32 s57, v255, 11
	v_max3_f32 v10, v10, v117, v118
	v_max3_f32 v10, v10, v119, v120
	v_cndmask_b32_e64 v19, v19, v179, s[56:57]
	v_readlane_b32 s56, v255, 12
	v_readlane_b32 s57, v255, 13
	v_max3_f32 v10, v10, v121, v122
	v_max3_f32 v10, v10, v123, v130
	v_cndmask_b32_e64 v20, v20, v179, s[56:57]
	v_readlane_b32 s56, v255, 14
	v_readlane_b32 s57, v255, 15
	v_max3_f32 v10, v10, v63, v111
	v_max3_f32 v10, v10, v110, v109
	v_cndmask_b32_e64 v21, v21, v179, s[56:57]
	v_readlane_b32 s56, v255, 16
	v_readlane_b32 s57, v255, 17
	v_max3_f32 v10, v10, v108, v107
	v_max3_f32 v10, v10, v106, v105
	v_cndmask_b32_e64 v22, v22, v179, s[56:57]
	v_readlane_b32 s56, v255, 18
	v_readlane_b32 s57, v255, 19
	v_max3_f32 v10, v10, v104, v103
	v_max3_f32 v10, v10, v101, v100
	v_cndmask_b32_e64 v23, v23, v179, s[56:57]
	v_readlane_b32 s56, v255, 20
	v_readlane_b32 s57, v255, 21
	v_max3_f32 v10, v10, v99, v98
	v_max3_f32 v10, v10, v97, v95
	v_cndmask_b32_e64 v24, v24, v179, s[56:57]
	v_readlane_b32 s56, v255, 22
	v_readlane_b32 s57, v255, 23
	v_max3_f32 v10, v10, v94, v93
	v_max3_f32 v10, v10, v91, v90
	v_cndmask_b32_e64 v25, v25, v179, s[56:57]
	v_readlane_b32 s56, v255, 24
	v_readlane_b32 s57, v255, 25
	v_max3_f32 v10, v10, v86, v87
	v_max3_f32 v10, v10, v88, v89
	v_cndmask_b32_e64 v26, v26, v179, s[56:57]
	v_readlane_b32 s56, v255, 26
	v_readlane_b32 s57, v255, 27
	v_max3_f32 v10, v10, v16, v17
	v_max3_f32 v10, v10, v18, v19
	v_cndmask_b32_e64 v27, v27, v179, s[56:57]
	v_readlane_b32 s56, v255, 28
	v_readlane_b32 s57, v255, 29
	v_max3_f32 v10, v10, v20, v21
	v_max3_f32 v10, v10, v22, v23
	v_cndmask_b32_e64 v28, v28, v179, s[56:57]
	v_readlane_b32 s56, v255, 30
	v_readlane_b32 s57, v255, 31
	v_max3_f32 v10, v10, v24, v25
	v_max3_f32 v10, v10, v26, v27
	v_cndmask_b32_e64 v29, v29, v179, s[56:57]
	v_readlane_b32 s56, v255, 32
	v_readlane_b32 s57, v255, 33
	v_max3_f32 v10, v10, v28, v29
	s_waitcnt vmcnt(0)
	v_mul_f32_e32 v33, 0x3fb8aa3b, v96
	v_cndmask_b32_e64 v30, v30, v179, s[56:57]
	v_readlane_b32 s56, v255, 2
	v_readlane_b32 s57, v255, 3
	v_lshl_add_u32 v115, s93, 6, v139
	v_lshl_or_b32 v114, s12, 6, v137
	v_cndmask_b32_e64 v31, v31, v179, s[56:57]
	v_max3_f32 v10, v10, v30, v31
	ds_bpermute_b32 v32, v112, v10
	s_waitcnt lgkmcnt(0)
	v_max_f32_e32 v32, v32, v32
	v_max_f32_e32 v10, v10, v32
	v_mul_f32_e32 v10, 0x3e38aa3b, v10
	v_max_f32_e32 v10, v10, v33
	v_fma_f32 v0, v0, s18, -v10
	v_exp_f32_e32 v0, v0
	v_fma_f32 v1, v1, s18, -v10
	v_exp_f32_e32 v1, v1
	v_fma_f32 v2, v2, s18, -v10
	v_exp_f32_e32 v2, v2
	v_fma_f32 v3, v3, s18, -v10
	v_exp_f32_e32 v3, v3
	v_fma_f32 v4, v4, s18, -v10
	v_add_f32_e32 v32, 0, v0
	v_exp_f32_e32 v4, v4
	v_fma_f32 v5, v5, s18, -v10
	v_add_f32_e32 v32, v1, v32
	v_exp_f32_e32 v5, v5
	v_fma_f32 v6, v6, s18, -v10
	v_add_f32_e32 v32, v2, v32
	v_exp_f32_e32 v6, v6
	v_fma_f32 v7, v7, s18, -v10
	v_add_f32_e32 v32, v3, v32
	v_exp_f32_e32 v7, v7
	v_add_f32_e32 v32, v4, v32
	v_add_f32_e32 v32, v5, v32
	v_add_f32_e32 v32, v6, v32
	v_fma_f32 v8, v8, s18, -v10
	v_add_f32_e32 v36, v7, v32
	v_exp_f32_e32 v32, v8
	v_fma_f32 v8, v9, s18, -v10
	v_exp_f32_e32 v33, v8
	v_fma_f32 v8, v34, s18, -v10
	v_exp_f32_e32 v34, v8
	v_fma_f32 v8, v11, s18, -v10
	v_exp_f32_e32 v35, v8
	v_fma_f32 v9, v12, s18, -v10
	v_add_f32_e32 v8, v32, v36
	v_exp_f32_e32 v36, v9
	v_fma_f32 v9, v13, s18, -v10
	v_add_f32_e32 v8, v33, v8
	v_exp_f32_e32 v37, v9
	v_fma_f32 v9, v14, s18, -v10
	v_add_f32_e32 v8, v34, v8
	v_exp_f32_e32 v38, v9
	v_fma_f32 v9, v15, s18, -v10
	v_add_f32_e32 v8, v35, v8
	v_exp_f32_e32 v40, v9
	v_fma_f32 v9, v48, s18, -v10
	v_add_f32_e32 v8, v36, v8
	v_exp_f32_e32 v39, v9
	v_fma_f32 v9, v49, s18, -v10
	v_add_f32_e32 v8, v37, v8
	v_exp_f32_e32 v41, v9
	v_fma_f32 v9, v50, s18, -v10
	v_add_f32_e32 v8, v38, v8
	v_exp_f32_e32 v42, v9
	v_fma_f32 v9, v51, s18, -v10
	v_add_f32_e32 v8, v40, v8
	v_exp_f32_e32 v43, v9
	v_fma_f32 v9, v52, s18, -v10
	v_add_f32_e32 v8, v39, v8
	v_exp_f32_e32 v44, v9
	v_fma_f32 v9, v53, s18, -v10
	v_add_f32_e32 v8, v41, v8
	v_exp_f32_e32 v45, v9
	v_fma_f32 v9, v54, s18, -v10
	v_add_f32_e32 v8, v42, v8
	v_exp_f32_e32 v46, v9
	v_fma_f32 v9, v55, s18, -v10
	v_add_f32_e32 v8, v43, v8
	v_exp_f32_e32 v48, v9
	v_fma_f32 v9, v56, s18, -v10
	v_add_f32_e32 v8, v44, v8
	v_exp_f32_e32 v47, v9
	v_fma_f32 v9, v57, s18, -v10
	v_add_f32_e32 v8, v45, v8
	v_exp_f32_e32 v49, v9
	v_fma_f32 v9, v58, s18, -v10
	v_add_f32_e32 v8, v46, v8
	v_exp_f32_e32 v50, v9
	v_fma_f32 v9, v59, s18, -v10
	v_add_f32_e32 v8, v48, v8
	v_exp_f32_e32 v51, v9
	v_fma_f32 v9, v60, s18, -v10
	v_add_f32_e32 v8, v47, v8
	v_exp_f32_e32 v52, v9
	v_fma_f32 v9, v61, s18, -v10
	v_add_f32_e32 v8, v49, v8
	v_exp_f32_e32 v53, v9
	v_fma_f32 v9, v62, s18, -v10
	v_add_f32_e32 v8, v50, v8
	v_exp_f32_e32 v54, v9
	v_fma_f32 v9, v116, s18, -v10
	v_add_f32_e32 v8, v51, v8
	v_exp_f32_e32 v56, v9
	v_fma_f32 v9, v117, s18, -v10
	v_add_f32_e32 v8, v52, v8
	v_exp_f32_e32 v55, v9
	v_fma_f32 v9, v118, s18, -v10
	v_add_f32_e32 v8, v53, v8
	v_exp_f32_e32 v57, v9
	v_fma_f32 v9, v119, s18, -v10
	v_add_f32_e32 v8, v54, v8
	v_exp_f32_e32 v58, v9
	v_fma_f32 v9, v120, s18, -v10
	v_add_f32_e32 v8, v56, v8
	v_exp_f32_e32 v59, v9
	v_fma_f32 v9, v121, s18, -v10
	v_add_f32_e32 v8, v55, v8
	v_exp_f32_e32 v60, v9
	v_fma_f32 v9, v122, s18, -v10
	v_add_f32_e32 v8, v57, v8
	v_exp_f32_e32 v61, v9
	v_fma_f32 v9, v123, s18, -v10
	v_add_f32_e32 v8, v58, v8
	v_exp_f32_e32 v62, v9
	v_fma_f32 v9, v130, s18, -v10
	v_add_f32_e32 v8, v59, v8
	v_exp_f32_e32 v64, v9
	v_fma_f32 v9, v63, s18, -v10
	v_add_f32_e32 v8, v60, v8
	v_exp_f32_e32 v63, v9
	v_fma_f32 v9, v111, s18, -v10
	v_add_f32_e32 v8, v61, v8
	v_exp_f32_e32 v65, v9
	v_fma_f32 v9, v110, s18, -v10
	v_add_f32_e32 v8, v62, v8
	v_exp_f32_e32 v66, v9
	v_fma_f32 v9, v109, s18, -v10
	v_add_f32_e32 v8, v64, v8
	v_exp_f32_e32 v67, v9
	v_fma_f32 v9, v108, s18, -v10
	v_add_f32_e32 v8, v63, v8
	v_exp_f32_e32 v68, v9
	v_fma_f32 v9, v107, s18, -v10
	v_add_f32_e32 v8, v65, v8
	v_exp_f32_e32 v69, v9
	v_fma_f32 v9, v106, s18, -v10
	v_add_f32_e32 v8, v66, v8
	v_exp_f32_e32 v70, v9
	v_fma_f32 v9, v105, s18, -v10
	v_add_f32_e32 v8, v67, v8
	v_exp_f32_e32 v72, v9
	v_fma_f32 v9, v104, s18, -v10
	v_add_f32_e32 v8, v68, v8
	v_exp_f32_e32 v71, v9
	v_fma_f32 v9, v103, s18, -v10
	v_add_f32_e32 v8, v69, v8
	v_exp_f32_e32 v73, v9
	v_fma_f32 v9, v101, s18, -v10
	v_add_f32_e32 v8, v70, v8
	v_exp_f32_e32 v74, v9
	v_fma_f32 v9, v100, s18, -v10
	v_add_f32_e32 v8, v72, v8
	v_exp_f32_e32 v75, v9
	v_fma_f32 v9, v99, s18, -v10
	v_add_f32_e32 v8, v71, v8
	v_exp_f32_e32 v76, v9
	v_fma_f32 v9, v98, s18, -v10
	v_add_f32_e32 v8, v73, v8
	v_exp_f32_e32 v77, v9
	v_fma_f32 v9, v97, s18, -v10
	v_add_f32_e32 v8, v74, v8
	v_exp_f32_e32 v78, v9
	v_fma_f32 v9, v95, s18, -v10
	v_add_f32_e32 v8, v75, v8
	v_exp_f32_e32 v80, v9
	v_fma_f32 v9, v94, s18, -v10
	v_add_f32_e32 v8, v76, v8
	v_exp_f32_e32 v79, v9
	v_fma_f32 v9, v93, s18, -v10
	v_add_f32_e32 v8, v77, v8
	v_exp_f32_e32 v81, v9
	v_fma_f32 v9, v91, s18, -v10
	v_add_f32_e32 v8, v78, v8
	v_exp_f32_e32 v82, v9
	v_fma_f32 v9, v90, s18, -v10
	v_add_f32_e32 v8, v80, v8
	v_exp_f32_e32 v83, v9
	v_fma_f32 v9, v86, s18, -v10
	v_add_f32_e32 v8, v79, v8
	v_exp_f32_e32 v86, v9
	v_fma_f32 v9, v87, s18, -v10
	v_add_f32_e32 v8, v81, v8
	v_exp_f32_e32 v87, v9
	v_fma_f32 v9, v88, s18, -v10
	v_add_f32_e32 v8, v82, v8
	v_exp_f32_e32 v88, v9
	v_fma_f32 v9, v89, s18, -v10
	v_add_f32_e32 v8, v83, v8
	v_exp_f32_e32 v90, v9
	v_fma_f32 v9, v16, s18, -v10
	v_add_f32_e32 v8, v86, v8
	v_exp_f32_e32 v89, v9
	v_fma_f32 v9, v17, s18, -v10
	v_add_f32_e32 v8, v87, v8
	v_exp_f32_e32 v91, v9
	v_fma_f32 v9, v18, s18, -v10
	v_add_f32_e32 v8, v88, v8
	v_exp_f32_e32 v93, v9
	v_fma_f32 v9, v19, s18, -v10
	v_add_f32_e32 v8, v90, v8
	v_exp_f32_e32 v94, v9
	v_fma_f32 v9, v20, s18, -v10
	v_add_f32_e32 v8, v89, v8
	v_exp_f32_e32 v95, v9
	v_fma_f32 v9, v21, s18, -v10
	v_add_f32_e32 v8, v91, v8
	v_exp_f32_e32 v97, v9
	v_fma_f32 v9, v22, s18, -v10
	v_add_f32_e32 v8, v93, v8
	v_exp_f32_e32 v98, v9
	v_fma_f32 v9, v23, s18, -v10
	v_add_f32_e32 v8, v94, v8
	v_exp_f32_e32 v100, v9
	v_fma_f32 v9, v24, s18, -v10
	v_add_f32_e32 v8, v95, v8
	v_exp_f32_e32 v99, v9
	v_fma_f32 v9, v25, s18, -v10
	v_add_f32_e32 v8, v97, v8
	v_exp_f32_e32 v101, v9
	v_fma_f32 v9, v26, s18, -v10
	v_add_f32_e32 v8, v98, v8
	v_exp_f32_e32 v103, v9
	v_fma_f32 v9, v27, s18, -v10
	v_add_f32_e32 v8, v100, v8
	v_exp_f32_e32 v104, v9
	v_fma_f32 v9, v28, s18, -v10
	v_add_f32_e32 v8, v99, v8
	v_exp_f32_e32 v105, v9
	v_fma_f32 v9, v29, s18, -v10
	v_add_f32_e32 v8, v101, v8
	v_exp_f32_e32 v106, v9
	v_fma_f32 v9, v30, s18, -v10
	v_add_f32_e32 v8, v103, v8
	v_exp_f32_e32 v107, v9
	v_fma_f32 v9, v31, s18, -v10
	v_add_f32_e32 v8, v104, v8
	v_exp_f32_e32 v108, v9
	v_add_f32_e32 v8, v105, v8
	v_add_f32_e32 v8, v106, v8
	v_add_f32_e32 v8, v107, v8
	v_add_f32_e32 v8, v108, v8
	ds_bpermute_b32 v9, v112, v8
	v_fma_f32 v10, v96, s13, -v10
	v_exp_f32_e32 v10, v10
	v_cvt_pk_bf16_f32 v0, v0, v1
	v_cvt_pk_bf16_f32 v1, v2, v3
	s_waitcnt lgkmcnt(0)
	v_add_f32_e32 v8, v8, v9
	v_add_f32_e32 v96, v10, v8
	v_div_scale_f32 v8, vcc, v96, v96, 1.0
	v_rcp_f32_e32 v9, v8
	v_cvt_pk_bf16_f32 v2, v4, v5
	v_cvt_pk_bf16_f32 v3, v6, v7
	v_cvt_pk_bf16_f32 v32, v32, v33
	v_fma_f32 v10, -v8, v9, 1.0
	v_fmac_f32_e32 v9, v10, v9
	v_div_scale_f32 v10, vcc, 1.0, v96, 1.0
	v_mul_f32_e32 v11, v10, v9
	v_fma_f32 v12, -v8, v11, v10
	v_fmac_f32_e32 v11, v12, v9
	v_fma_f32 v8, -v8, v11, v10
	v_lshl_add_u32 v12, s15, 6, v139
	v_div_fmas_f32 v109, v8, v9, v11
	v_add_u32_e32 v8, v12, v157
	v_add_u32_e32 v110, 0x9000, v8
	ds_read2_b64 v[8:11], v110 offset1:2
	v_add_u32_e32 v4, v12, v158
	v_add_u32_e32 v119, 0x9000, v4
	ds_read2_b64 v[110:113], v110 offset0:4 offset1:6
	s_waitcnt lgkmcnt(1)
	v_mfma_f32_32x32x16_bf16 v[16:31], v[8:11], v[0:3], 0
	ds_read2_b64 v[4:7], v119 offset1:2
	v_cvt_pk_bf16_f32 v33, v34, v35
	v_cvt_pk_bf16_f32 v34, v36, v37
	v_cvt_pk_bf16_f32 v35, v38, v40
	v_cvt_pk_bf16_f32 v36, v39, v41
	v_cvt_pk_bf16_f32 v37, v42, v43
	v_cvt_pk_bf16_f32 v38, v44, v45
	s_waitcnt lgkmcnt(1)
	v_mfma_f32_32x32x16_bf16 v[16:31], v[110:113], v[32:35], v[16:31]
	ds_read2_b64 v[110:113], v119 offset0:4 offset1:6
	v_cvt_pk_bf16_f32 v39, v46, v48
	v_lshl_add_u32 v116, s94, 6, v139
	v_lshl_add_u32 v117, s95, 6, v139
	v_lshl_add_u32 v118, s24, 6, v139
	v_readlane_b32 s12, v254, 52
	v_readlane_b32 s13, v254, 53
	s_waitcnt lgkmcnt(1)
	v_mfma_f32_32x32x16_bf16 v[0:15], v[4:7], v[0:3], 0
	v_lshlrev_b32_e32 v130, 1, v114
	s_waitcnt lgkmcnt(0)
	v_mfma_f32_32x32x16_bf16 v[0:15], v[110:113], v[32:35], v[0:15]
	v_add_u32_e32 v32, v115, v157
	v_add_u32_e32 v40, 0x9000, v32
	ds_read2_b64 v[32:35], v40 offset1:2
	s_waitcnt lgkmcnt(0)
	v_mfma_f32_32x32x16_bf16 v[16:31], v[32:35], v[36:39], v[16:31]
	v_add_u32_e32 v32, v115, v158
	v_add_u32_e32 v41, 0x9000, v32
	ds_read2_b64 v[32:35], v41 offset1:2
	s_waitcnt lgkmcnt(0)
	v_mfma_f32_32x32x16_bf16 v[0:15], v[32:35], v[36:39], v[0:15]
	ds_read2_b64 v[32:35], v40 offset0:4 offset1:6
	v_cvt_pk_bf16_f32 v36, v47, v49
	v_cvt_pk_bf16_f32 v37, v50, v51
	v_cvt_pk_bf16_f32 v38, v52, v53
	v_cvt_pk_bf16_f32 v39, v54, v56
	s_waitcnt lgkmcnt(0)
	s_nop 0
	v_mfma_f32_32x32x16_bf16 v[16:31], v[32:35], v[36:39], v[16:31]
	ds_read2_b64 v[32:35], v41 offset0:4 offset1:6
	s_waitcnt lgkmcnt(0)
	v_mfma_f32_32x32x16_bf16 v[0:15], v[32:35], v[36:39], v[0:15]
	v_add_u32_e32 v32, v116, v157
	v_add_u32_e32 v40, 0x9000, v32
	ds_read2_b64 v[32:35], v40 offset1:2
	v_cvt_pk_bf16_f32 v36, v55, v57
	v_cvt_pk_bf16_f32 v37, v58, v59
	v_cvt_pk_bf16_f32 v38, v60, v61
	v_cvt_pk_bf16_f32 v39, v62, v64
	s_waitcnt lgkmcnt(0)
	s_nop 0
	v_mfma_f32_32x32x16_bf16 v[16:31], v[32:35], v[36:39], v[16:31]
	v_add_u32_e32 v32, v116, v158
	v_add_u32_e32 v41, 0x9000, v32
	ds_read2_b64 v[32:35], v41 offset1:2
	s_waitcnt lgkmcnt(0)
	v_mfma_f32_32x32x16_bf16 v[0:15], v[32:35], v[36:39], v[0:15]
	ds_read2_b64 v[32:35], v40 offset0:4 offset1:6
	v_cvt_pk_bf16_f32 v36, v63, v65
	v_cvt_pk_bf16_f32 v37, v66, v67
	v_cvt_pk_bf16_f32 v38, v68, v69
	v_cvt_pk_bf16_f32 v39, v70, v72
	s_waitcnt lgkmcnt(0)
	s_nop 0
	v_mfma_f32_32x32x16_bf16 v[16:31], v[32:35], v[36:39], v[16:31]
	ds_read2_b64 v[32:35], v41 offset0:4 offset1:6
	s_waitcnt lgkmcnt(0)
	v_mfma_f32_32x32x16_bf16 v[0:15], v[32:35], v[36:39], v[0:15]
	v_add_u32_e32 v32, v117, v157
	v_add_u32_e32 v40, 0x9000, v32
	ds_read2_b64 v[32:35], v40 offset1:2
	v_cvt_pk_bf16_f32 v36, v71, v73
	v_cvt_pk_bf16_f32 v37, v74, v75
	v_cvt_pk_bf16_f32 v38, v76, v77
	v_cvt_pk_bf16_f32 v39, v78, v80
	s_waitcnt lgkmcnt(0)
	s_nop 0
	v_mfma_f32_32x32x16_bf16 v[16:31], v[32:35], v[36:39], v[16:31]
	v_add_u32_e32 v32, v117, v158
	v_add_u32_e32 v41, 0x9000, v32
	ds_read2_b64 v[32:35], v41 offset1:2
	s_waitcnt lgkmcnt(0)
	v_mfma_f32_32x32x16_bf16 v[0:15], v[32:35], v[36:39], v[0:15]
	ds_read2_b64 v[32:35], v40 offset0:4 offset1:6
	v_cvt_pk_bf16_f32 v36, v79, v81
	v_cvt_pk_bf16_f32 v37, v82, v83
	v_cvt_pk_bf16_f32 v38, v86, v87
	v_cvt_pk_bf16_f32 v39, v88, v90
	s_waitcnt lgkmcnt(0)
	s_nop 0
	v_mfma_f32_32x32x16_bf16 v[16:31], v[32:35], v[36:39], v[16:31]
	ds_read2_b64 v[32:35], v41 offset0:4 offset1:6
	s_waitcnt lgkmcnt(0)
	v_mfma_f32_32x32x16_bf16 v[0:15], v[32:35], v[36:39], v[0:15]
	v_add_u32_e32 v32, v118, v157
	v_add_u32_e32 v40, 0x9000, v32
	ds_read2_b64 v[32:35], v40 offset1:2
	v_cvt_pk_bf16_f32 v36, v89, v91
	v_cvt_pk_bf16_f32 v37, v93, v94
	v_cvt_pk_bf16_f32 v38, v95, v97
	v_cvt_pk_bf16_f32 v39, v98, v100
	s_waitcnt lgkmcnt(0)
	s_nop 0
	v_mfma_f32_32x32x16_bf16 v[16:31], v[32:35], v[36:39], v[16:31]
	v_add_u32_e32 v32, v118, v158
	v_add_u32_e32 v41, 0x9000, v32
	ds_read2_b64 v[32:35], v41 offset1:2
	s_waitcnt lgkmcnt(0)
	v_mfma_f32_32x32x16_bf16 v[0:15], v[32:35], v[36:39], v[0:15]
	ds_read2_b64 v[32:35], v40 offset0:4 offset1:6
	v_cvt_pk_bf16_f32 v36, v99, v101
	v_cvt_pk_bf16_f32 v37, v103, v104
	v_cvt_pk_bf16_f32 v38, v105, v106
	v_cvt_pk_bf16_f32 v39, v107, v108
	s_waitcnt lgkmcnt(0)
	s_nop 0
	v_mfma_f32_32x32x16_bf16 v[16:31], v[32:35], v[36:39], v[16:31]
	ds_read2_b64 v[32:35], v41 offset0:4 offset1:6
	s_waitcnt lgkmcnt(0)
	v_mfma_f32_32x32x16_bf16 v[0:15], v[32:35], v[36:39], v[0:15]
	v_div_fixup_f32 v32, v109, v96, 1.0
	v_lshl_add_u64 v[34:35], s[12:13], 0, v[84:85]
	s_nop 6
	v_pk_mul_f32 v[16:17], v[16:17], v[32:33] op_sel_hi:[1,0]
	v_pk_mul_f32 v[18:19], v[18:19], v[32:33] op_sel_hi:[1,0]
	v_pk_mul_f32 v[20:21], v[20:21], v[32:33] op_sel_hi:[1,0]
	v_pk_mul_f32 v[22:23], v[22:23], v[32:33] op_sel_hi:[1,0]
	v_pk_mul_f32 v[24:25], v[24:25], v[32:33] op_sel_hi:[1,0]
	v_pk_mul_f32 v[26:27], v[26:27], v[32:33] op_sel_hi:[1,0]
	v_pk_mul_f32 v[28:29], v[28:29], v[32:33] op_sel_hi:[1,0]
	v_pk_mul_f32 v[30:31], v[30:31], v[32:33] op_sel_hi:[1,0]
	v_and_b32_e32 v152, 32, v102
	v_lshrrev_b32_e32 v152, 2, v152
	v_mov_b32_e32 v153, 0
	v_lshl_add_u64 v[200:201], v[34:35], 0, v[130:131]
	v_pk_mul_f32 v[0:1], v[0:1], v[32:33] op_sel_hi:[1,0]
	v_pk_mul_f32 v[2:3], v[2:3], v[32:33] op_sel_hi:[1,0]
	v_pk_mul_f32 v[4:5], v[4:5], v[32:33] op_sel_hi:[1,0]
	v_pk_mul_f32 v[6:7], v[6:7], v[32:33] op_sel_hi:[1,0]
	v_pk_mul_f32 v[8:9], v[8:9], v[32:33] op_sel_hi:[1,0]
	v_pk_mul_f32 v[10:11], v[10:11], v[32:33] op_sel_hi:[1,0]
	v_pk_mul_f32 v[12:13], v[12:13], v[32:33] op_sel_hi:[1,0]
	v_pk_mul_f32 v[14:15], v[14:15], v[32:33] op_sel_hi:[1,0]
	v_cvt_pk_bf16_f32 v144, v16, v17
	v_cvt_pk_bf16_f32 v145, v18, v19
	v_cvt_pk_bf16_f32 v146, v20, v21
	v_cvt_pk_bf16_f32 v147, v22, v23
	v_cvt_pk_bf16_f32 v148, v24, v25
	v_cvt_pk_bf16_f32 v149, v26, v27
	v_cvt_pk_bf16_f32 v150, v28, v29
	v_cvt_pk_bf16_f32 v151, v30, v31
	v_cvt_pk_bf16_f32 v192, v0, v1
	v_cvt_pk_bf16_f32 v193, v2, v3
	v_cvt_pk_bf16_f32 v194, v4, v5
	v_cvt_pk_bf16_f32 v195, v6, v7
	v_cvt_pk_bf16_f32 v196, v8, v9
	v_cvt_pk_bf16_f32 v197, v10, v11
	v_cvt_pk_bf16_f32 v198, v12, v13
	v_cvt_pk_bf16_f32 v199, v14, v15
	v_lshl_add_u64 v[200:201], v[200:201], 0, v[152:153]
	s_nop 1
	v_permlane32_swap_b32_e32 v144, v146
	v_permlane32_swap_b32_e32 v145, v147
	v_permlane32_swap_b32_e32 v148, v150
	v_permlane32_swap_b32_e32 v149, v151
	v_permlane32_swap_b32_e32 v192, v194
	v_permlane32_swap_b32_e32 v193, v195
	v_permlane32_swap_b32_e32 v196, v198
	v_permlane32_swap_b32_e32 v197, v199
	global_store_dwordx4 v[200:201], v[144:147], off
	global_store_dwordx4 v[200:201], v[148:151], off offset:32
	global_store_dwordx4 v[200:201], v[192:195], off offset:64
	global_store_dwordx4 v[200:201], v[196:199], off offset:96


	s_mov_b64 s[12:13], 0
